# odd K-tile load segment: the eight invariant-address B-fragment ds_reads issue first, ahead of the A-address VALU (on top of the segment trim)
# baseline (speedup 1.0000x reference)
; #define PG8_STAGE(bufoff, gbase, voff) do { _Pragma("unroll") for (int _i = 0; _i < 2; ++_i) \
;         __builtin_amdgcn_global_load_lds((const unsigned*)((const char*)(gbase) + (voff)[_i]), (PG8_LAS unsigned*)(lds + (bufoff) + ldsw + _i * 8192), 16, 0, 0); } while (0)
; #define PG8_LDA(dst, b, h) do { _Pragma("unroll") for (int m = 0; m < 4; ++m) _Pragma("unroll") for (int k = 0; k < 2; ++k) dst[m][k] = *(const PG8_LAS bf16x8*)(lds + PG8_SA(b, h) + aoff + m * 2048 + k * 1024); } while (0)
; #define PG8_LDB(dst, b, h) do { _Pragma("unroll") for (int n = 0; n < 2; ++n) _Pragma("unroll") for (int k = 0; k < 2; ++k) dst[n][k] = *(const PG8_LAS bf16x8*)(lds + PG8_SB(b, h) + boff + n * 2048 + k * 1024); } while (0)
; #define PG8_MMA(ai, bj, At, Bt) do { __builtin_amdgcn_s_setprio(1); _Pragma("unroll") for (int m = 0; m < 4; ++m) _Pragma("unroll") for (int n = 0; n < 2; ++n) _Pragma("unroll") for (int k = 0; k < 2; ++k) \
;         acc[ai][bj][m][n] = __builtin_amdgcn_mfma_f32_16x16x32_bf16(Bt[n][k], At[m][k], acc[ai][bj][m][n], 0, 0, 0); __builtin_amdgcn_s_setprio(0); } while (0)
; #define PG8_WAIT_V(n) asm volatile("s_waitcnt vmcnt(" #n ")" ::: "memory")
; #define PG8_WAIT_L(n) asm volatile("s_waitcnt lgkmcnt(" #n ")" ::: "memory")
; #define PG8_BAR __builtin_amdgcn_s_barrier()
; #define PG8_SCHED __builtin_amdgcn_sched_barrier(0)
; template <class Epi, class Sched, bool ALIGN_EPI = false, bool SP2 = false>
; __device__ __forceinline__ void gemm_phase(PG8_LAS unsigned char* lds, const Gemm g, const Sched& S, const Epi& E) {
;     ...
;             PG8_LDB(B0, 1, 0); PG8_LDB(B1, 1, 1); PG8_SCHED; PG8_LDA(At, 1, 0); PG8_STAGE(PG8_SA(0, 1), a2 + hstep, voffA);
;             PG8_WAIT_V(8); PG8_WAIT_L(0); PG8_BAR; PG8_MMA(0, 0, At, B0); PG8_MMA(0, 1, At, B1); PG8_BAR; PG8_SCHED;
.Lpz1_mid:
	ds_read_b128 v[186:189], v152 offset:32768
	ds_read_b128 v[190:193], v152 offset:33792
	ds_read_b128 v[194:197], v152 offset:34816
	ds_read_b128 v[198:201], v152 offset:35840
	ds_read_b128 v[202:205], v152 offset:36864
	ds_read_b128 v[206:209], v152 offset:37888
	ds_read_b128 v[210:213], v152 offset:38912
	ds_read_b128 v[214:217], v152 offset:39936
	s_add_i32 s55, 0, 0x18000
	v_add_u32_e32 v138, s55, v149
	s_add_i32 s56, 0, 0x1c000
	ds_read_b128 v[154:157], v138
	ds_read_b128 v[158:161], v138 offset:1024
	ds_read_b128 v[162:165], v138 offset:2048
	ds_read_b128 v[166:169], v138 offset:3072
	v_add_u32_e32 v138, s56, v149
	ds_read_b128 v[170:173], v138
	ds_read_b128 v[174:177], v138 offset:1024
	ds_read_b128 v[178:181], v138 offset:2048
	ds_read_b128 v[182:185], v138 offset:3072
	s_add_u32 s26, s26, 0x40000
	s_addc_u32 s27, s27, 0
	s_mov_b32 m0, s39
	v_lshl_add_u64 v[228:229], s[26:27], 0, v[136:137]
	global_load_lds_dwordx4 v[228:229], off
	v_lshl_add_u64 v[228:229], s[26:27], 0, v[132:133]
	s_mov_b32 m0, s40
	s_nop 0
	global_load_lds_dwordx4 v[228:229], off
	s_waitcnt vmcnt(8)
	s_waitcnt lgkmcnt(0)
	s_barrier
	s_setprio 1
	v_mfma_f32_16x16x32_bf16 v[126:129], v[154:157], v[186:189], v[126:129]
	v_mfma_f32_16x16x32_bf16 v[122:125], v[162:165], v[186:189], v[122:125]
	v_mfma_f32_16x16x32_bf16 v[110:113], v[154:157], v[194:197], v[110:113]
	v_mfma_f32_16x16x32_bf16 v[106:109], v[162:165], v[194:197], v[106:109]
	v_mfma_f32_16x16x32_bf16 v[94:97], v[154:157], v[202:205], v[94:97]
	v_mfma_f32_16x16x32_bf16 v[90:93], v[162:165], v[202:205], v[90:93]
	v_mfma_f32_16x16x32_bf16 v[78:81], v[154:157], v[210:213], v[78:81]
	v_mfma_f32_16x16x32_bf16 v[74:77], v[162:165], v[210:213], v[74:77]
	v_mfma_f32_16x16x32_bf16 v[126:129], v[158:161], v[190:193], v[126:129]
	v_mfma_f32_16x16x32_bf16 v[122:125], v[166:169], v[190:193], v[122:125]
	v_mfma_f32_16x16x32_bf16 v[110:113], v[158:161], v[198:201], v[110:113]
	v_mfma_f32_16x16x32_bf16 v[106:109], v[166:169], v[198:201], v[106:109]
	v_mfma_f32_16x16x32_bf16 v[94:97], v[158:161], v[206:209], v[94:97]
	v_mfma_f32_16x16x32_bf16 v[90:93], v[166:169], v[206:209], v[90:93]
	v_mfma_f32_16x16x32_bf16 v[78:81], v[158:161], v[214:217], v[78:81]
	v_mfma_f32_16x16x32_bf16 v[74:77], v[166:169], v[214:217], v[74:77]
	v_mfma_f32_16x16x32_bf16 v[118:121], v[170:173], v[186:189], v[118:121]
	v_mfma_f32_16x16x32_bf16 v[114:117], v[178:181], v[186:189], v[114:117]
	v_mfma_f32_16x16x32_bf16 v[102:105], v[170:173], v[194:197], v[102:105]
	v_mfma_f32_16x16x32_bf16 v[98:101], v[178:181], v[194:197], v[98:101]
	v_mfma_f32_16x16x32_bf16 v[86:89], v[170:173], v[202:205], v[86:89]
	v_mfma_f32_16x16x32_bf16 v[82:85], v[178:181], v[202:205], v[82:85]
	v_mfma_f32_16x16x32_bf16 v[70:73], v[170:173], v[210:213], v[70:73]
	v_mfma_f32_16x16x32_bf16 v[66:69], v[178:181], v[210:213], v[66:69]
	v_mfma_f32_16x16x32_bf16 v[118:121], v[174:177], v[190:193], v[118:121]
	v_mfma_f32_16x16x32_bf16 v[114:117], v[182:185], v[190:193], v[114:117]
	v_mfma_f32_16x16x32_bf16 v[102:105], v[174:177], v[198:201], v[102:105]
	v_mfma_f32_16x16x32_bf16 v[98:101], v[182:185], v[198:201], v[98:101]
	v_mfma_f32_16x16x32_bf16 v[86:89], v[174:177], v[206:209], v[86:89]
	v_mfma_f32_16x16x32_bf16 v[82:85], v[182:185], v[206:209], v[82:85]
	v_mfma_f32_16x16x32_bf16 v[70:73], v[174:177], v[214:217], v[70:73]
	v_mfma_f32_16x16x32_bf16 v[66:69], v[182:185], v[214:217], v[66:69]
	s_setprio 0
	s_barrier
; #define PG8_STAGE(bufoff, gbase, voff) do { _Pragma("unroll") for (int _i = 0; _i < 2; ++_i) \
;         __builtin_amdgcn_global_load_lds((const unsigned*)((const char*)(gbase) + (voff)[_i]), (PG8_LAS unsigned*)(lds + (bufoff) + ldsw + _i * 8192), 16, 0, 0); } while (0)
; #define PG8_LDA(dst, b, h) do { _Pragma("unroll") for (int m = 0; m < 4; ++m) _Pragma("unroll") for (int k = 0; k < 2; ++k) dst[m][k] = *(const PG8_LAS bf16x8*)(lds + PG8_SA(b, h) + aoff + m * 2048 + k * 1024); } while (0)
; #define PG8_MMA(ai, bj, At, Bt) do { __builtin_amdgcn_s_setprio(1); _Pragma("unroll") for (int m = 0; m < 4; ++m) _Pragma("unroll") for (int n = 0; n < 2; ++n) _Pragma("unroll") for (int k = 0; k < 2; ++k) \
;         acc[ai][bj][m][n] = __builtin_amdgcn_mfma_f32_16x16x32_bf16(Bt[n][k], At[m][k], acc[ai][bj][m][n], 0, 0, 0); __builtin_amdgcn_s_setprio(0); } while (0)
; #define PG8_WAIT_V(n) asm volatile("s_waitcnt vmcnt(" #n ")" ::: "memory")
; #define PG8_WAIT_L(n) asm volatile("s_waitcnt lgkmcnt(" #n ")" ::: "memory")
; #define PG8_BAR __builtin_amdgcn_s_barrier()
; #define PG8_SCHED __builtin_amdgcn_sched_barrier(0)
; template <class Epi, class Sched, bool ALIGN_EPI = false, bool SP2 = false>
; __device__ __forceinline__ void gemm_phase(PG8_LAS unsigned char* lds, const Gemm g, const Sched& S, const Epi& E) {
;     ...
;             PG8_LDA(At, 1, 1); PG8_STAGE(PG8_SB(1, 0), b3, voffB); PG8_STAGE(PG8_SB(1, 1), b3 + hstep, voffB); PG8_STAGE(PG8_SA(1, 0), a3, voffA);
;             PG8_WAIT_V(8); PG8_WAIT_L(0); PG8_BAR; PG8_MMA(1, 0, At, B0); PG8_MMA(1, 1, At, B1); PG8_BAR; PG8_SCHED;
;     ...
;         if constexpr (ALIGN_EPI) { if (wr == 0) PG8_BAR; }
	s_add_i32 s26, s55, s34
	v_lshl_add_u64 v[218:219], v[218:219], 0, s[8:9]
	s_mov_b32 m0, s26
	ds_read_b128 v[186:189], v152 offset:49152
	ds_read_b128 v[190:193], v152 offset:50176
	ds_read_b128 v[194:197], v152 offset:51200
	ds_read_b128 v[198:201], v152 offset:52224
	ds_read_b128 v[202:205], v152 offset:53248
	ds_read_b128 v[206:209], v152 offset:54272
	ds_read_b128 v[210:213], v152 offset:55296
	ds_read_b128 v[214:217], v152 offset:56320
	global_load_lds_dwordx4 v[218:219], off
	s_add_i32 m0, s26, 0x2000
	s_add_u32 s24, s24, 0x40080
	v_lshl_add_u64 v[218:219], v[222:223], 0, s[8:9]
	s_addc_u32 s25, s25, 0
	s_add_i32 s26, s56, s34
	global_load_lds_dwordx4 v[218:219], off
	v_lshl_add_u64 v[218:219], s[24:25], 0, v[134:135]
	s_mov_b32 m0, s26
	s_nop 0
	global_load_lds_dwordx4 v[218:219], off
	v_lshl_add_u64 v[218:219], s[24:25], 0, v[130:131]
	s_add_i32 m0, s26, 0x2000
	s_nop 0
	global_load_lds_dwordx4 v[218:219], off
	v_lshl_add_u64 v[218:219], v[224:225], 0, s[8:9]
	s_mov_b32 m0, s42
	s_nop 0
	global_load_lds_dwordx4 v[218:219], off
	v_lshl_add_u64 v[218:219], v[226:227], 0, s[8:9]
	s_mov_b32 m0, s43
	s_nop 0
	global_load_lds_dwordx4 v[218:219], off
	s_waitcnt vmcnt(8)
	s_waitcnt lgkmcnt(0)
	s_barrier
	s_setprio 1
	v_mfma_f32_16x16x32_bf16 v[62:65], v[154:157], v[186:189], v[62:65]
	v_mfma_f32_16x16x32_bf16 v[58:61], v[162:165], v[186:189], v[58:61]
	v_mfma_f32_16x16x32_bf16 v[46:49], v[154:157], v[194:197], v[46:49]
	v_mfma_f32_16x16x32_bf16 v[42:45], v[162:165], v[194:197], v[42:45]
	v_mfma_f32_16x16x32_bf16 v[30:33], v[154:157], v[202:205], v[30:33]
	v_mfma_f32_16x16x32_bf16 v[26:29], v[162:165], v[202:205], v[26:29]
	v_mfma_f32_16x16x32_bf16 v[14:17], v[154:157], v[210:213], v[14:17]
	v_mfma_f32_16x16x32_bf16 v[10:13], v[162:165], v[210:213], v[10:13]
	v_mfma_f32_16x16x32_bf16 v[62:65], v[158:161], v[190:193], v[62:65]
	v_mfma_f32_16x16x32_bf16 v[58:61], v[166:169], v[190:193], v[58:61]
	v_mfma_f32_16x16x32_bf16 v[46:49], v[158:161], v[198:201], v[46:49]
	v_mfma_f32_16x16x32_bf16 v[42:45], v[166:169], v[198:201], v[42:45]
	v_mfma_f32_16x16x32_bf16 v[30:33], v[158:161], v[206:209], v[30:33]
	v_mfma_f32_16x16x32_bf16 v[26:29], v[166:169], v[206:209], v[26:29]
	v_mfma_f32_16x16x32_bf16 v[14:17], v[158:161], v[214:217], v[14:17]
	v_mfma_f32_16x16x32_bf16 v[10:13], v[166:169], v[214:217], v[10:13]
	v_mfma_f32_16x16x32_bf16 v[54:57], v[170:173], v[186:189], v[54:57]
	v_mfma_f32_16x16x32_bf16 v[50:53], v[178:181], v[186:189], v[50:53]
	v_mfma_f32_16x16x32_bf16 v[38:41], v[170:173], v[194:197], v[38:41]
	v_mfma_f32_16x16x32_bf16 v[34:37], v[178:181], v[194:197], v[34:37]
	v_mfma_f32_16x16x32_bf16 v[22:25], v[170:173], v[202:205], v[22:25]
	v_mfma_f32_16x16x32_bf16 v[18:21], v[178:181], v[202:205], v[18:21]
	v_mfma_f32_16x16x32_bf16 v[6:9], v[170:173], v[210:213], v[6:9]
	v_mfma_f32_16x16x32_bf16 v[2:5], v[178:181], v[210:213], v[2:5]
	v_mfma_f32_16x16x32_bf16 v[54:57], v[174:177], v[190:193], v[54:57]
	v_mfma_f32_16x16x32_bf16 v[50:53], v[182:185], v[190:193], v[50:53]
	v_mfma_f32_16x16x32_bf16 v[38:41], v[174:177], v[198:201], v[38:41]
	v_mfma_f32_16x16x32_bf16 v[34:37], v[182:185], v[198:201], v[34:37]
	v_mfma_f32_16x16x32_bf16 v[22:25], v[174:177], v[206:209], v[22:25]
	v_mfma_f32_16x16x32_bf16 v[18:21], v[182:185], v[206:209], v[18:21]
	v_mfma_f32_16x16x32_bf16 v[6:9], v[174:177], v[214:217], v[6:9]
	v_mfma_f32_16x16x32_bf16 v[2:5], v[182:185], v[214:217], v[2:5]
	s_setprio 0
	s_barrier
	s_add_i32 s54, s54, 2
	s_add_u32 s22, s22, 0x100
	s_addc_u32 s23, s23, 0
	s_add_u32 s52, s52, 0x100
	s_addc_u32 s53, s53, 0
	s_cmp_gt_u32 s54, 13
	s_cbranch_scc0 .LBB0_208
	s_and_b64 vcc, exec, s[10:11]
	s_cbranch_vccz .LBB0_211
	s_barrier

; #define PG8_STAGE(bufoff, gbase, voff) do { _Pragma("unroll") for (int _i = 0; _i < 2; ++_i) \
;         __builtin_amdgcn_global_load_lds((const unsigned*)((const char*)(gbase) + (voff)[_i]), (PG8_LAS unsigned*)(lds + (bufoff) + ldsw + _i * 8192), 16, 0, 0); } while (0)
; #define PG8_LDA(dst, b, h) do { _Pragma("unroll") for (int m = 0; m < 4; ++m) _Pragma("unroll") for (int k = 0; k < 2; ++k) dst[m][k] = *(const PG8_LAS bf16x8*)(lds + PG8_SA(b, h) + aoff + m * 2048 + k * 1024); } while (0)
; #define PG8_LDB(dst, b, h) do { _Pragma("unroll") for (int n = 0; n < 2; ++n) _Pragma("unroll") for (int k = 0; k < 2; ++k) dst[n][k] = *(const PG8_LAS bf16x8*)(lds + PG8_SB(b, h) + boff + n * 2048 + k * 1024); } while (0)
; #define PG8_MMA(ai, bj, At, Bt) do { __builtin_amdgcn_s_setprio(1); _Pragma("unroll") for (int m = 0; m < 4; ++m) _Pragma("unroll") for (int n = 0; n < 2; ++n) _Pragma("unroll") for (int k = 0; k < 2; ++k) \
;         acc[ai][bj][m][n] = __builtin_amdgcn_mfma_f32_16x16x32_bf16(Bt[n][k], At[m][k], acc[ai][bj][m][n], 0, 0, 0); __builtin_amdgcn_s_setprio(0); } while (0)
; #define PG8_WAIT_V(n) asm volatile("s_waitcnt vmcnt(" #n ")" ::: "memory")
; #define PG8_WAIT_L(n) asm volatile("s_waitcnt lgkmcnt(" #n ")" ::: "memory")
; #define PG8_BAR __builtin_amdgcn_s_barrier()
; #define PG8_SCHED __builtin_amdgcn_sched_barrier(0)
; template <class Epi, class Sched, bool ALIGN_EPI = false, bool SP2 = false>
; __device__ __forceinline__ void gemm_phase(PG8_LAS unsigned char* lds, const Gemm g, const Sched& S, const Epi& E) {
;     ...
;             PG8_LDB(B0, 1, 0); PG8_LDB(B1, 1, 1); PG8_SCHED; PG8_LDA(At, 1, 0); PG8_STAGE(PG8_SA(0, 1), a2 + hstep, voffA);
;             PG8_WAIT_V(8); PG8_WAIT_L(0); PG8_BAR; PG8_MMA(0, 0, At, B0); PG8_MMA(0, 1, At, B1); PG8_BAR; PG8_SCHED;
.Lpz2_mid:
	ds_read_b128 v[180:183], v225 offset:32768
	ds_read_b128 v[184:187], v225 offset:33792
	ds_read_b128 v[188:191], v225 offset:34816
	ds_read_b128 v[192:195], v225 offset:35840
	ds_read_b128 v[196:199], v225 offset:36864
	ds_read_b128 v[200:203], v225 offset:37888
	ds_read_b128 v[204:207], v225 offset:38912
	ds_read_b128 v[208:211], v225 offset:39936
	s_add_i32 s42, 0, 0x18000
	s_add_i32 s43, 0, 0x1c000
	v_add_u32_e32 v142, s42, v222
	v_add_u32_e32 v154, s43, v222
	ds_read_b128 v[130:133], v142
	ds_read_b128 v[134:137], v142 offset:1024
	ds_read_b128 v[138:141], v142 offset:2048
	ds_read_b128 v[142:145], v142 offset:3072
	ds_read_b128 v[164:167], v154
	ds_read_b128 v[168:171], v154 offset:1024
	ds_read_b128 v[172:175], v154 offset:2048
	ds_read_b128 v[176:179], v154 offset:3072
	s_add_u32 s4, s36, 0xb0000
	s_addc_u32 s5, s37, 0
	s_mov_b32 m0, s53
	v_lshl_add_u64 v[216:217], s[4:5], 0, v[146:147]
	global_load_lds_dwordx4 v[216:217], off
	v_lshl_add_u64 v[216:217], s[4:5], 0, v[150:151]
	s_mov_b32 m0, s54
	s_nop 0
	global_load_lds_dwordx4 v[216:217], off
	s_waitcnt vmcnt(8)
	s_waitcnt lgkmcnt(0)
	s_barrier
	s_setprio 1
	v_mfma_f32_16x16x32_bf16 v[126:129], v[130:133], v[180:183], v[126:129]
	v_mfma_f32_16x16x32_bf16 v[122:125], v[138:141], v[180:183], v[122:125]
	v_mfma_f32_16x16x32_bf16 v[110:113], v[130:133], v[188:191], v[110:113]
	v_mfma_f32_16x16x32_bf16 v[106:109], v[138:141], v[188:191], v[106:109]
	v_mfma_f32_16x16x32_bf16 v[94:97], v[130:133], v[196:199], v[94:97]
	v_mfma_f32_16x16x32_bf16 v[90:93], v[138:141], v[196:199], v[90:93]
	v_mfma_f32_16x16x32_bf16 v[78:81], v[130:133], v[204:207], v[78:81]
	v_mfma_f32_16x16x32_bf16 v[74:77], v[138:141], v[204:207], v[74:77]
	v_mfma_f32_16x16x32_bf16 v[126:129], v[134:137], v[184:187], v[126:129]
	v_mfma_f32_16x16x32_bf16 v[122:125], v[142:145], v[184:187], v[122:125]
	v_mfma_f32_16x16x32_bf16 v[110:113], v[134:137], v[192:195], v[110:113]
	v_mfma_f32_16x16x32_bf16 v[106:109], v[142:145], v[192:195], v[106:109]
	v_mfma_f32_16x16x32_bf16 v[94:97], v[134:137], v[200:203], v[94:97]
	v_mfma_f32_16x16x32_bf16 v[90:93], v[142:145], v[200:203], v[90:93]
	v_mfma_f32_16x16x32_bf16 v[78:81], v[134:137], v[208:211], v[78:81]
	v_mfma_f32_16x16x32_bf16 v[74:77], v[142:145], v[208:211], v[74:77]
	v_mfma_f32_16x16x32_bf16 v[118:121], v[164:167], v[180:183], v[118:121]
	v_mfma_f32_16x16x32_bf16 v[114:117], v[172:175], v[180:183], v[114:117]
	v_mfma_f32_16x16x32_bf16 v[102:105], v[164:167], v[188:191], v[102:105]
	v_mfma_f32_16x16x32_bf16 v[98:101], v[172:175], v[188:191], v[98:101]
	v_mfma_f32_16x16x32_bf16 v[86:89], v[164:167], v[196:199], v[86:89]
	v_mfma_f32_16x16x32_bf16 v[82:85], v[172:175], v[196:199], v[82:85]
	v_mfma_f32_16x16x32_bf16 v[70:73], v[164:167], v[204:207], v[70:73]
	v_mfma_f32_16x16x32_bf16 v[66:69], v[172:175], v[204:207], v[66:69]
	v_mfma_f32_16x16x32_bf16 v[118:121], v[168:171], v[184:187], v[118:121]
	v_mfma_f32_16x16x32_bf16 v[114:117], v[176:179], v[184:187], v[114:117]
	v_mfma_f32_16x16x32_bf16 v[102:105], v[168:171], v[192:195], v[102:105]
	v_mfma_f32_16x16x32_bf16 v[98:101], v[176:179], v[192:195], v[98:101]
	v_mfma_f32_16x16x32_bf16 v[86:89], v[168:171], v[200:203], v[86:89]
	v_mfma_f32_16x16x32_bf16 v[82:85], v[176:179], v[200:203], v[82:85]
	v_mfma_f32_16x16x32_bf16 v[70:73], v[168:171], v[208:211], v[70:73]
	v_mfma_f32_16x16x32_bf16 v[66:69], v[176:179], v[208:211], v[66:69]
	s_setprio 0
	s_barrier
; #define PG8_STAGE(bufoff, gbase, voff) do { _Pragma("unroll") for (int _i = 0; _i < 2; ++_i) \
;         __builtin_amdgcn_global_load_lds((const unsigned*)((const char*)(gbase) + (voff)[_i]), (PG8_LAS unsigned*)(lds + (bufoff) + ldsw + _i * 8192), 16, 0, 0); } while (0)
; #define PG8_LDA(dst, b, h) do { _Pragma("unroll") for (int m = 0; m < 4; ++m) _Pragma("unroll") for (int k = 0; k < 2; ++k) dst[m][k] = *(const PG8_LAS bf16x8*)(lds + PG8_SA(b, h) + aoff + m * 2048 + k * 1024); } while (0)
; #define PG8_MMA(ai, bj, At, Bt) do { __builtin_amdgcn_s_setprio(1); _Pragma("unroll") for (int m = 0; m < 4; ++m) _Pragma("unroll") for (int n = 0; n < 2; ++n) _Pragma("unroll") for (int k = 0; k < 2; ++k) \
;         acc[ai][bj][m][n] = __builtin_amdgcn_mfma_f32_16x16x32_bf16(Bt[n][k], At[m][k], acc[ai][bj][m][n], 0, 0, 0); __builtin_amdgcn_s_setprio(0); } while (0)
; #define PG8_WAIT_V(n) asm volatile("s_waitcnt vmcnt(" #n ")" ::: "memory")
; #define PG8_WAIT_L(n) asm volatile("s_waitcnt lgkmcnt(" #n ")" ::: "memory")
; #define PG8_BAR __builtin_amdgcn_s_barrier()
; #define PG8_SCHED __builtin_amdgcn_sched_barrier(0)
; template <class Epi, class Sched, bool ALIGN_EPI = false, bool SP2 = false>
; __device__ __forceinline__ void gemm_phase(PG8_LAS unsigned char* lds, const Gemm g, const Sched& S, const Epi& E) {
;     ...
;             PG8_LDA(At, 1, 1); PG8_STAGE(PG8_SB(1, 0), b3, voffB); PG8_STAGE(PG8_SB(1, 1), b3 + hstep, voffB); PG8_STAGE(PG8_SA(1, 0), a3, voffA);
;             PG8_WAIT_V(8); PG8_WAIT_L(0); PG8_BAR; PG8_MMA(1, 0, At, B0); PG8_MMA(1, 1, At, B1); PG8_BAR; PG8_SCHED;
;     ...
;         if constexpr (ALIGN_EPI) { if (wr == 0) PG8_BAR; }
	s_add_i32 s4, s42, s50
	v_lshl_add_u64 v[160:161], v[160:161], 0, s[22:23]
	s_mov_b32 m0, s4
	ds_read_b128 v[180:183], v225 offset:49152
	ds_read_b128 v[184:187], v225 offset:50176
	ds_read_b128 v[188:191], v225 offset:51200
	ds_read_b128 v[192:195], v225 offset:52224
	ds_read_b128 v[196:199], v225 offset:53248
	ds_read_b128 v[200:203], v225 offset:54272
	ds_read_b128 v[204:207], v225 offset:55296
	ds_read_b128 v[208:211], v225 offset:56320
	global_load_lds_dwordx4 v[160:161], off
	s_add_i32 m0, s4, 0x2000
	s_add_u32 s4, s6, 0xb0080
	v_lshl_add_u64 v[160:161], v[162:163], 0, s[22:23]
	s_addc_u32 s5, s7, 0
	s_add_i32 s6, s43, s50
	global_load_lds_dwordx4 v[160:161], off
	v_lshl_add_u64 v[160:161], s[4:5], 0, v[148:149]
	s_mov_b32 m0, s6
	s_nop 0
	global_load_lds_dwordx4 v[160:161], off
	v_lshl_add_u64 v[160:161], s[4:5], 0, v[152:153]
	s_add_i32 m0, s6, 0x2000
	s_nop 0
	global_load_lds_dwordx4 v[160:161], off
	v_lshl_add_u64 v[160:161], v[212:213], 0, s[24:25]
	s_mov_b32 m0, s63
	s_nop 0
	global_load_lds_dwordx4 v[160:161], off
	v_lshl_add_u64 v[160:161], v[214:215], 0, s[24:25]
	s_mov_b32 m0, s64
	s_nop 0
	global_load_lds_dwordx4 v[160:161], off
	s_waitcnt vmcnt(8)
	s_waitcnt lgkmcnt(0)
	s_barrier
	s_setprio 1
	v_mfma_f32_16x16x32_bf16 v[62:65], v[130:133], v[180:183], v[62:65]
	v_mfma_f32_16x16x32_bf16 v[58:61], v[138:141], v[180:183], v[58:61]
	v_mfma_f32_16x16x32_bf16 v[46:49], v[130:133], v[188:191], v[46:49]
	v_mfma_f32_16x16x32_bf16 v[42:45], v[138:141], v[188:191], v[42:45]
	v_mfma_f32_16x16x32_bf16 v[30:33], v[130:133], v[196:199], v[30:33]
	v_mfma_f32_16x16x32_bf16 v[26:29], v[138:141], v[196:199], v[26:29]
	v_mfma_f32_16x16x32_bf16 v[14:17], v[130:133], v[204:207], v[14:17]
	v_mfma_f32_16x16x32_bf16 v[10:13], v[138:141], v[204:207], v[10:13]
	v_mfma_f32_16x16x32_bf16 v[62:65], v[134:137], v[184:187], v[62:65]
	v_mfma_f32_16x16x32_bf16 v[58:61], v[142:145], v[184:187], v[58:61]
	v_mfma_f32_16x16x32_bf16 v[46:49], v[134:137], v[192:195], v[46:49]
	v_mfma_f32_16x16x32_bf16 v[42:45], v[142:145], v[192:195], v[42:45]
	v_mfma_f32_16x16x32_bf16 v[30:33], v[134:137], v[200:203], v[30:33]
	v_mfma_f32_16x16x32_bf16 v[26:29], v[142:145], v[200:203], v[26:29]
	v_mfma_f32_16x16x32_bf16 v[14:17], v[134:137], v[208:211], v[14:17]
	v_mfma_f32_16x16x32_bf16 v[10:13], v[142:145], v[208:211], v[10:13]
	v_mfma_f32_16x16x32_bf16 v[54:57], v[164:167], v[180:183], v[54:57]
	v_mfma_f32_16x16x32_bf16 v[50:53], v[172:175], v[180:183], v[50:53]
	v_mfma_f32_16x16x32_bf16 v[38:41], v[164:167], v[188:191], v[38:41]
	v_mfma_f32_16x16x32_bf16 v[34:37], v[172:175], v[188:191], v[34:37]
	v_mfma_f32_16x16x32_bf16 v[22:25], v[164:167], v[196:199], v[22:25]
	v_mfma_f32_16x16x32_bf16 v[18:21], v[172:175], v[196:199], v[18:21]
	v_mfma_f32_16x16x32_bf16 v[6:9], v[164:167], v[204:207], v[6:9]
	v_mfma_f32_16x16x32_bf16 v[2:5], v[172:175], v[204:207], v[2:5]
	v_mfma_f32_16x16x32_bf16 v[54:57], v[168:171], v[184:187], v[54:57]
	v_mfma_f32_16x16x32_bf16 v[50:53], v[176:179], v[184:187], v[50:53]
	v_mfma_f32_16x16x32_bf16 v[38:41], v[168:171], v[192:195], v[38:41]
	v_mfma_f32_16x16x32_bf16 v[34:37], v[176:179], v[192:195], v[34:37]
	v_mfma_f32_16x16x32_bf16 v[22:25], v[168:171], v[200:203], v[22:25]
	v_mfma_f32_16x16x32_bf16 v[18:21], v[176:179], v[200:203], v[18:21]
	v_mfma_f32_16x16x32_bf16 v[6:9], v[168:171], v[208:211], v[6:9]
	v_mfma_f32_16x16x32_bf16 v[2:5], v[176:179], v[208:211], v[2:5]
	s_setprio 0
	s_barrier
	s_add_i32 s41, s41, 2
	s_add_u32 s39, s39, 0x100
	s_addc_u32 s40, s40, 0
	s_cmp_gt_u32 s41, 41
	s_mov_b64 s[4:5], s[0:1]
	s_cbranch_scc0 .LBB0_289
	s_and_b64 vcc, exec, s[26:27]
	s_cbranch_vccz .LBB0_292
	s_barrier

; #define PG8_STAGE(bufoff, gbase, voff) do { _Pragma("unroll") for (int _i = 0; _i < 2; ++_i) \
;         __builtin_amdgcn_global_load_lds((const unsigned*)((const char*)(gbase) + (voff)[_i]), (PG8_LAS unsigned*)(lds + (bufoff) + ldsw + _i * 8192), 16, 0, 0); } while (0)
; #define PG8_LDA(dst, b, h) do { _Pragma("unroll") for (int m = 0; m < 4; ++m) _Pragma("unroll") for (int k = 0; k < 2; ++k) dst[m][k] = *(const PG8_LAS bf16x8*)(lds + PG8_SA(b, h) + aoff + m * 2048 + k * 1024); } while (0)
; #define PG8_LDB(dst, b, h) do { _Pragma("unroll") for (int n = 0; n < 2; ++n) _Pragma("unroll") for (int k = 0; k < 2; ++k) dst[n][k] = *(const PG8_LAS bf16x8*)(lds + PG8_SB(b, h) + boff + n * 2048 + k * 1024); } while (0)
; #define PG8_MMA(ai, bj, At, Bt) do { __builtin_amdgcn_s_setprio(1); _Pragma("unroll") for (int m = 0; m < 4; ++m) _Pragma("unroll") for (int n = 0; n < 2; ++n) _Pragma("unroll") for (int k = 0; k < 2; ++k) \
;         acc[ai][bj][m][n] = __builtin_amdgcn_mfma_f32_16x16x32_bf16(Bt[n][k], At[m][k], acc[ai][bj][m][n], 0, 0, 0); __builtin_amdgcn_s_setprio(0); } while (0)
; #define PG8_WAIT_V(n) asm volatile("s_waitcnt vmcnt(" #n ")" ::: "memory")
; #define PG8_WAIT_L(n) asm volatile("s_waitcnt lgkmcnt(" #n ")" ::: "memory")
; #define PG8_BAR __builtin_amdgcn_s_barrier()
; #define PG8_SCHED __builtin_amdgcn_sched_barrier(0)
; template <class Epi, class Sched, bool ALIGN_EPI = false, bool SP2 = false>
; __device__ __forceinline__ void gemm_phase(PG8_LAS unsigned char* lds, const Gemm g, const Sched& S, const Epi& E) {
;     ...
;             PG8_LDB(B0, 1, 0); PG8_LDB(B1, 1, 1); PG8_SCHED; PG8_LDA(At, 1, 0); PG8_STAGE(PG8_SA(0, 1), a2 + hstep, voffA);
;             PG8_WAIT_V(8); PG8_WAIT_L(0); PG8_BAR; PG8_MMA(0, 0, At, B0); PG8_MMA(0, 1, At, B1); PG8_BAR; PG8_SCHED;
;             PG8_LDA(At, 1, 1); PG8_STAGE(PG8_SB(1, 0), b3, voffB); PG8_STAGE(PG8_SB(1, 1), b3 + hstep, voffB); PG8_STAGE(PG8_SA(1, 0), a3, voffA);
;             PG8_WAIT_V(8); PG8_WAIT_L(0); PG8_BAR; PG8_MMA(1, 0, At, B0); PG8_MMA(1, 1, At, B1); PG8_BAR; PG8_SCHED;
.Lpz3_mid:
	ds_read_b128 v[212:215], v210 offset:32768
	ds_read_b128 v[216:219], v210 offset:33792
	ds_read_b128 v[222:225], v210 offset:34816
	ds_read_b128 v[226:229], v210 offset:35840
	ds_read_b128 v[230:233], v210 offset:36864
	ds_read_b128 v[234:237], v210 offset:37888
	ds_read_b128 v[238:241], v210 offset:38912
	ds_read_b128 v[242:245], v210 offset:39936
	s_add_i32 s29, 0, 0x18000
	v_add_u32_e32 v122, s29, v203
	s_add_i32 vcc_lo, 0, 0x1c000
	ds_read_b128 v[146:149], v122
	ds_read_b128 v[150:153], v122 offset:1024
	ds_read_b128 v[154:157], v122 offset:2048
	ds_read_b128 v[158:161], v122 offset:3072
	v_add_u32_e32 v122, vcc_lo, v203
	ds_read_b128 v[162:165], v122
	ds_read_b128 v[166:169], v122 offset:1024
	ds_read_b128 v[170:173], v122 offset:2048
	ds_read_b128 v[174:177], v122 offset:3072
	s_add_u32 s60, s60, 0x40000
	s_addc_u32 s61, s61, 0
	s_mov_b32 m0, s75
	v_lshl_add_u64 v[122:123], s[60:61], 0, v[178:179]
	global_load_lds_dwordx4 v[122:123], off
	v_lshl_add_u64 v[122:123], s[60:61], 0, v[182:183]
	s_mov_b32 m0, s76
	s_nop 0
	global_load_lds_dwordx4 v[122:123], off
	s_waitcnt vmcnt(8)
	s_waitcnt lgkmcnt(0)
	s_barrier
	s_setprio 1
	v_mfma_f32_16x16x32_bf16 v[42:45], v[146:149], v[212:215], v[42:45]
	v_mfma_f32_16x16x32_bf16 v[142:145], v[150:153], v[216:219], v[42:45]
	v_mfma_f32_16x16x32_bf16 v[42:45], v[154:157], v[212:215], v[46:49]
	v_mfma_f32_16x16x32_bf16 v[138:141], v[158:161], v[216:219], v[42:45]
	v_mfma_f32_16x16x32_bf16 v[42:45], v[146:149], v[222:225], v[50:53]
	v_mfma_f32_16x16x32_bf16 v[126:129], v[150:153], v[226:229], v[42:45]
	v_mfma_f32_16x16x32_bf16 v[42:45], v[154:157], v[222:225], v[54:57]
	v_mfma_f32_16x16x32_bf16 v[122:125], v[158:161], v[226:229], v[42:45]
	v_mfma_f32_16x16x32_bf16 v[42:45], v[146:149], v[230:233], v[110:113]
	v_mfma_f32_16x16x32_bf16 v[110:113], v[150:153], v[234:237], v[42:45]
	v_mfma_f32_16x16x32_bf16 v[42:45], v[154:157], v[230:233], v[106:109]
	v_mfma_f32_16x16x32_bf16 v[106:109], v[158:161], v[234:237], v[42:45]
	v_mfma_f32_16x16x32_bf16 v[42:45], v[146:149], v[238:241], v[94:97]
	v_mfma_f32_16x16x32_bf16 v[94:97], v[150:153], v[242:245], v[42:45]
	v_mfma_f32_16x16x32_bf16 v[42:45], v[154:157], v[238:241], v[90:93]
	v_mfma_f32_16x16x32_bf16 v[90:93], v[158:161], v[242:245], v[42:45]
	v_mfma_f32_16x16x32_bf16 v[42:45], v[162:165], v[212:215], v[134:137]
	v_mfma_f32_16x16x32_bf16 v[134:137], v[166:169], v[216:219], v[42:45]
	v_mfma_f32_16x16x32_bf16 v[42:45], v[170:173], v[212:215], v[130:133]
	v_mfma_f32_16x16x32_bf16 v[130:133], v[174:177], v[216:219], v[42:45]
	v_mfma_f32_16x16x32_bf16 v[42:45], v[162:165], v[222:225], v[118:121]
	v_mfma_f32_16x16x32_bf16 v[118:121], v[166:169], v[226:229], v[42:45]
	v_mfma_f32_16x16x32_bf16 v[42:45], v[170:173], v[222:225], v[114:117]
	v_mfma_f32_16x16x32_bf16 v[114:117], v[174:177], v[226:229], v[42:45]
	v_mfma_f32_16x16x32_bf16 v[42:45], v[162:165], v[230:233], v[102:105]
	v_mfma_f32_16x16x32_bf16 v[102:105], v[166:169], v[234:237], v[42:45]
	v_mfma_f32_16x16x32_bf16 v[42:45], v[170:173], v[230:233], v[98:101]
	v_mfma_f32_16x16x32_bf16 v[98:101], v[174:177], v[234:237], v[42:45]
	v_mfma_f32_16x16x32_bf16 v[42:45], v[162:165], v[238:241], v[86:89]
	v_mfma_f32_16x16x32_bf16 v[86:89], v[166:169], v[242:245], v[42:45]
	v_mfma_f32_16x16x32_bf16 v[42:45], v[170:173], v[238:241], v[82:85]
	v_mfma_f32_16x16x32_bf16 v[82:85], v[174:177], v[242:245], v[42:45]
	s_setprio 0
	s_barrier
	s_add_i32 s29, s29, s68
	v_lshl_add_u64 v[204:205], v[204:205], 0, s[38:39]
	s_mov_b32 m0, s29
	s_nop 1
	ds_read_b128 v[42:45], v210 offset:49152
	ds_read_b128 v[46:49], v210 offset:50176
	ds_read_b128 v[50:53], v210 offset:51200
	ds_read_b128 v[54:57], v210 offset:52224
	ds_read_b128 v[212:215], v210 offset:53248
	ds_read_b128 v[216:219], v210 offset:54272
	ds_read_b128 v[222:225], v210 offset:55296
	ds_read_b128 v[226:229], v210 offset:56320
	global_load_lds_dwordx4 v[204:205], off
	s_add_i32 m0, s29, 0x2000
	s_add_u32 s58, s58, 0x40080
	v_lshl_add_u64 v[204:205], v[246:247], 0, s[38:39]
	s_addc_u32 s59, s59, 0
	s_add_i32 s29, vcc_lo, s68
	global_load_lds_dwordx4 v[204:205], off
	v_lshl_add_u64 v[204:205], s[58:59], 0, v[180:181]
	s_mov_b32 m0, s29
	s_nop 0
	global_load_lds_dwordx4 v[204:205], off
	v_lshl_add_u64 v[204:205], s[58:59], 0, v[184:185]
	s_add_i32 m0, s29, 0x2000
	s_nop 0
	global_load_lds_dwordx4 v[204:205], off
	v_lshl_add_u64 v[204:205], v[248:249], 0, s[38:39]
	s_mov_b32 m0, s81
	s_nop 0
	global_load_lds_dwordx4 v[204:205], off
	v_lshl_add_u64 v[204:205], v[250:251], 0, s[38:39]
	s_mov_b32 m0, s82
	s_nop 0
	global_load_lds_dwordx4 v[204:205], off
	s_waitcnt vmcnt(8)
	s_waitcnt lgkmcnt(0)
	s_barrier
	s_setprio 1
	v_mfma_f32_16x16x32_bf16 v[78:81], v[146:149], v[42:45], v[78:81]
	v_mfma_f32_16x16x32_bf16 v[74:77], v[154:157], v[42:45], v[74:77]
	v_mfma_f32_16x16x32_bf16 v[62:65], v[146:149], v[50:53], v[62:65]
	v_mfma_f32_16x16x32_bf16 v[58:61], v[154:157], v[50:53], v[58:61]
	v_mfma_f32_16x16x32_bf16 v[30:33], v[146:149], v[212:215], v[30:33]
	v_mfma_f32_16x16x32_bf16 v[26:29], v[154:157], v[212:215], v[26:29]
	v_mfma_f32_16x16x32_bf16 v[14:17], v[146:149], v[222:225], v[14:17]
	v_mfma_f32_16x16x32_bf16 v[10:13], v[154:157], v[222:225], v[10:13]
	v_mfma_f32_16x16x32_bf16 v[78:81], v[150:153], v[46:49], v[78:81]
	v_mfma_f32_16x16x32_bf16 v[74:77], v[158:161], v[46:49], v[74:77]
	v_mfma_f32_16x16x32_bf16 v[62:65], v[150:153], v[54:57], v[62:65]
	v_mfma_f32_16x16x32_bf16 v[58:61], v[158:161], v[54:57], v[58:61]
	v_mfma_f32_16x16x32_bf16 v[30:33], v[150:153], v[216:219], v[30:33]
	v_mfma_f32_16x16x32_bf16 v[26:29], v[158:161], v[216:219], v[26:29]
	v_mfma_f32_16x16x32_bf16 v[14:17], v[150:153], v[226:229], v[14:17]
	v_mfma_f32_16x16x32_bf16 v[10:13], v[158:161], v[226:229], v[10:13]
	v_mfma_f32_16x16x32_bf16 v[70:73], v[162:165], v[42:45], v[70:73]
	v_mfma_f32_16x16x32_bf16 v[42:45], v[170:173], v[42:45], v[66:69]
	v_mfma_f32_16x16x32_bf16 v[38:41], v[162:165], v[50:53], v[38:41]
	v_mfma_f32_16x16x32_bf16 v[34:37], v[170:173], v[50:53], v[34:37]
	v_mfma_f32_16x16x32_bf16 v[22:25], v[162:165], v[212:215], v[22:25]
	v_mfma_f32_16x16x32_bf16 v[18:21], v[170:173], v[212:215], v[18:21]
	v_mfma_f32_16x16x32_bf16 v[6:9], v[162:165], v[222:225], v[6:9]
	v_mfma_f32_16x16x32_bf16 v[2:5], v[170:173], v[222:225], v[2:5]
	v_mfma_f32_16x16x32_bf16 v[70:73], v[166:169], v[46:49], v[70:73]
	v_mfma_f32_16x16x32_bf16 v[66:69], v[174:177], v[46:49], v[42:45]
	v_mfma_f32_16x16x32_bf16 v[38:41], v[166:169], v[54:57], v[38:41]
	v_mfma_f32_16x16x32_bf16 v[34:37], v[174:177], v[54:57], v[34:37]
	v_mfma_f32_16x16x32_bf16 v[22:25], v[166:169], v[216:219], v[22:25]
	v_mfma_f32_16x16x32_bf16 v[18:21], v[174:177], v[216:219], v[18:21]
	v_mfma_f32_16x16x32_bf16 v[6:9], v[166:169], v[226:229], v[6:9]
	v_mfma_f32_16x16x32_bf16 v[2:5], v[174:177], v[226:229], v[2:5]
	s_setprio 0
	s_barrier
	s_add_i32 s29, s28, 2
	s_add_u32 s56, s56, 0x100
	s_addc_u32 s57, s57, 0
	s_cmp_gt_u32 s28, 13
	s_mov_b32 s28, s29
	s_cbranch_scc1 .LBB0_442

; #define PG8_STAGE(bufoff, gbase, voff) do { _Pragma("unroll") for (int _i = 0; _i < 2; ++_i) \
;         __builtin_amdgcn_global_load_lds((const unsigned*)((const char*)(gbase) + (voff)[_i]), (PG8_LAS unsigned*)(lds + (bufoff) + ldsw + _i * 8192), 16, 0, 0); } while (0)
; #define PG8_LDA(dst, b, h) do { _Pragma("unroll") for (int m = 0; m < 4; ++m) _Pragma("unroll") for (int k = 0; k < 2; ++k) dst[m][k] = *(const PG8_LAS bf16x8*)(lds + PG8_SA(b, h) + aoff + m * 2048 + k * 1024); } while (0)
; #define PG8_LDB(dst, b, h) do { _Pragma("unroll") for (int n = 0; n < 2; ++n) _Pragma("unroll") for (int k = 0; k < 2; ++k) dst[n][k] = *(const PG8_LAS bf16x8*)(lds + PG8_SB(b, h) + boff + n * 2048 + k * 1024); } while (0)
; #define PG8_MMA(ai, bj, At, Bt) do { __builtin_amdgcn_s_setprio(1); _Pragma("unroll") for (int m = 0; m < 4; ++m) _Pragma("unroll") for (int n = 0; n < 2; ++n) _Pragma("unroll") for (int k = 0; k < 2; ++k) \
;         acc[ai][bj][m][n] = __builtin_amdgcn_mfma_f32_16x16x32_bf16(Bt[n][k], At[m][k], acc[ai][bj][m][n], 0, 0, 0); __builtin_amdgcn_s_setprio(0); } while (0)
; #define PG8_WAIT_V(n) asm volatile("s_waitcnt vmcnt(" #n ")" ::: "memory")
; #define PG8_WAIT_L(n) asm volatile("s_waitcnt lgkmcnt(" #n ")" ::: "memory")
; #define PG8_BAR __builtin_amdgcn_s_barrier()
; #define PG8_SCHED __builtin_amdgcn_sched_barrier(0)
; template <class Epi, class Sched, bool ALIGN_EPI = false, bool SP2 = false>
; __device__ __forceinline__ void gemm_phase(PG8_LAS unsigned char* lds, const Gemm g, const Sched& S, const Epi& E) {
;     ...
;             PG8_LDB(B0, 1, 0); PG8_LDB(B1, 1, 1); PG8_SCHED; PG8_LDA(At, 1, 0); PG8_STAGE(PG8_SA(0, 1), a2 + hstep, voffA);
;             PG8_WAIT_V(8); PG8_WAIT_L(0); PG8_BAR; PG8_MMA(0, 0, At, B0); PG8_MMA(0, 1, At, B1); PG8_BAR; PG8_SCHED;
.Lpz4_mid:
	ds_read_b128 v[180:183], v216 offset:32768
	ds_read_b128 v[184:187], v216 offset:33792
	ds_read_b128 v[188:191], v216 offset:34816
	ds_read_b128 v[192:195], v216 offset:35840
	ds_read_b128 v[196:199], v216 offset:36864
	ds_read_b128 v[200:203], v216 offset:37888
	ds_read_b128 v[204:207], v216 offset:38912
	ds_read_b128 v[208:211], v216 offset:39936
	s_add_i32 s42, 0, 0x18000
	s_add_i32 s43, 0, 0x1c000
	v_add_u32_e32 v70, s42, v213
	v_add_u32_e32 v162, s43, v213
	ds_read_b128 v[58:61], v70
	ds_read_b128 v[62:65], v70 offset:1024
	ds_read_b128 v[66:69], v70 offset:2048
	ds_read_b128 v[70:73], v70 offset:3072
	ds_read_b128 v[146:149], v162
	ds_read_b128 v[150:153], v162 offset:1024
	ds_read_b128 v[172:175], v162 offset:2048
	ds_read_b128 v[176:179], v162 offset:3072
	s_add_u32 s36, s36, 0x40000
	s_addc_u32 s37, s37, 0
	s_mov_b32 m0, s53
	v_lshl_add_u64 v[228:229], s[36:37], 0, v[154:155]
	global_load_lds_dwordx4 v[228:229], off
	v_lshl_add_u64 v[228:229], s[36:37], 0, v[158:159]
	s_mov_b32 m0, s54
	s_nop 0
	global_load_lds_dwordx4 v[228:229], off
	s_waitcnt vmcnt(8)
	s_waitcnt lgkmcnt(0)
	s_barrier
	s_setprio 1
	v_mfma_f32_16x16x32_bf16 v[142:145], v[58:61], v[180:183], v[142:145]
	v_mfma_f32_16x16x32_bf16 v[138:141], v[66:69], v[180:183], v[138:141]
	v_mfma_f32_16x16x32_bf16 v[126:129], v[58:61], v[188:191], v[126:129]
	v_mfma_f32_16x16x32_bf16 v[122:125], v[66:69], v[188:191], v[122:125]
	v_mfma_f32_16x16x32_bf16 v[110:113], v[58:61], v[196:199], v[110:113]
	v_mfma_f32_16x16x32_bf16 v[106:109], v[66:69], v[196:199], v[106:109]
	v_mfma_f32_16x16x32_bf16 v[94:97], v[58:61], v[204:207], v[94:97]
	v_mfma_f32_16x16x32_bf16 v[90:93], v[66:69], v[204:207], v[90:93]
	v_mfma_f32_16x16x32_bf16 v[142:145], v[62:65], v[184:187], v[142:145]
	v_mfma_f32_16x16x32_bf16 v[138:141], v[70:73], v[184:187], v[138:141]
	v_mfma_f32_16x16x32_bf16 v[126:129], v[62:65], v[192:195], v[126:129]
	v_mfma_f32_16x16x32_bf16 v[122:125], v[70:73], v[192:195], v[122:125]
	v_mfma_f32_16x16x32_bf16 v[110:113], v[62:65], v[200:203], v[110:113]
	v_mfma_f32_16x16x32_bf16 v[106:109], v[70:73], v[200:203], v[106:109]
	v_mfma_f32_16x16x32_bf16 v[94:97], v[62:65], v[208:211], v[94:97]
	v_mfma_f32_16x16x32_bf16 v[90:93], v[70:73], v[208:211], v[90:93]
	v_mfma_f32_16x16x32_bf16 v[134:137], v[146:149], v[180:183], v[134:137]
	v_mfma_f32_16x16x32_bf16 v[130:133], v[172:175], v[180:183], v[130:133]
	v_mfma_f32_16x16x32_bf16 v[118:121], v[146:149], v[188:191], v[118:121]
	v_mfma_f32_16x16x32_bf16 v[114:117], v[172:175], v[188:191], v[114:117]
	v_mfma_f32_16x16x32_bf16 v[102:105], v[146:149], v[196:199], v[102:105]
	v_mfma_f32_16x16x32_bf16 v[98:101], v[172:175], v[196:199], v[98:101]
	v_mfma_f32_16x16x32_bf16 v[86:89], v[146:149], v[204:207], v[86:89]
	v_mfma_f32_16x16x32_bf16 v[82:85], v[172:175], v[204:207], v[82:85]
	v_mfma_f32_16x16x32_bf16 v[134:137], v[150:153], v[184:187], v[134:137]
	v_mfma_f32_16x16x32_bf16 v[130:133], v[176:179], v[184:187], v[130:133]
	v_mfma_f32_16x16x32_bf16 v[118:121], v[150:153], v[192:195], v[118:121]
	v_mfma_f32_16x16x32_bf16 v[114:117], v[176:179], v[192:195], v[114:117]
	v_mfma_f32_16x16x32_bf16 v[102:105], v[150:153], v[200:203], v[102:105]
	v_mfma_f32_16x16x32_bf16 v[98:101], v[176:179], v[200:203], v[98:101]
	v_mfma_f32_16x16x32_bf16 v[86:89], v[150:153], v[208:211], v[86:89]
	v_mfma_f32_16x16x32_bf16 v[82:85], v[176:179], v[208:211], v[82:85]
	s_setprio 0
	s_barrier
; #define PG8_STAGE(bufoff, gbase, voff) do { _Pragma("unroll") for (int _i = 0; _i < 2; ++_i) \
;         __builtin_amdgcn_global_load_lds((const unsigned*)((const char*)(gbase) + (voff)[_i]), (PG8_LAS unsigned*)(lds + (bufoff) + ldsw + _i * 8192), 16, 0, 0); } while (0)
; #define PG8_LDA(dst, b, h) do { _Pragma("unroll") for (int m = 0; m < 4; ++m) _Pragma("unroll") for (int k = 0; k < 2; ++k) dst[m][k] = *(const PG8_LAS bf16x8*)(lds + PG8_SA(b, h) + aoff + m * 2048 + k * 1024); } while (0)
; #define PG8_MMA(ai, bj, At, Bt) do { __builtin_amdgcn_s_setprio(1); _Pragma("unroll") for (int m = 0; m < 4; ++m) _Pragma("unroll") for (int n = 0; n < 2; ++n) _Pragma("unroll") for (int k = 0; k < 2; ++k) \
;         acc[ai][bj][m][n] = __builtin_amdgcn_mfma_f32_16x16x32_bf16(Bt[n][k], At[m][k], acc[ai][bj][m][n], 0, 0, 0); __builtin_amdgcn_s_setprio(0); } while (0)
; #define PG8_WAIT_V(n) asm volatile("s_waitcnt vmcnt(" #n ")" ::: "memory")
; #define PG8_WAIT_L(n) asm volatile("s_waitcnt lgkmcnt(" #n ")" ::: "memory")
; #define PG8_BAR __builtin_amdgcn_s_barrier()
; #define PG8_SCHED __builtin_amdgcn_sched_barrier(0)
; template <class Epi, class Sched, bool ALIGN_EPI = false, bool SP2 = false>
; __device__ __forceinline__ void gemm_phase(PG8_LAS unsigned char* lds, const Gemm g, const Sched& S, const Epi& E) {
;     ...
;             PG8_LDA(At, 1, 1); PG8_STAGE(PG8_SB(1, 0), b3, voffB); PG8_STAGE(PG8_SB(1, 1), b3 + hstep, voffB); PG8_STAGE(PG8_SA(1, 0), a3, voffA);
;             PG8_WAIT_V(8); PG8_WAIT_L(0); PG8_BAR; PG8_MMA(1, 0, At, B0); PG8_MMA(1, 1, At, B1); PG8_BAR; PG8_SCHED;
;     ...
;         if constexpr (ALIGN_EPI) { if (wr == 0) PG8_BAR; }
	s_add_i32 s36, s42, s50
	v_lshl_add_u64 v[218:219], v[218:219], 0, s[20:21]
	s_mov_b32 m0, s36
	ds_read_b128 v[180:183], v216 offset:49152
	ds_read_b128 v[184:187], v216 offset:50176
	ds_read_b128 v[188:191], v216 offset:51200
	ds_read_b128 v[192:195], v216 offset:52224
	ds_read_b128 v[196:199], v216 offset:53248
	ds_read_b128 v[200:203], v216 offset:54272
	ds_read_b128 v[204:207], v216 offset:55296
	ds_read_b128 v[208:211], v216 offset:56320
	global_load_lds_dwordx4 v[218:219], off
	s_add_i32 m0, s36, 0x2000
	s_add_u32 s6, s6, 0x40080
	v_lshl_add_u64 v[218:219], v[222:223], 0, s[20:21]
	s_addc_u32 s7, s7, 0
	s_add_i32 s36, s43, s50
	global_load_lds_dwordx4 v[218:219], off
	v_lshl_add_u64 v[218:219], s[6:7], 0, v[156:157]
	s_mov_b32 m0, s36
	s_nop 0
	global_load_lds_dwordx4 v[218:219], off
	v_lshl_add_u64 v[218:219], s[6:7], 0, v[160:161]
	s_add_i32 m0, s36, 0x2000
	s_nop 0
	global_load_lds_dwordx4 v[218:219], off
	v_lshl_add_u64 v[218:219], v[224:225], 0, s[20:21]
	s_mov_b32 m0, s63
	s_nop 0
	global_load_lds_dwordx4 v[218:219], off
	v_lshl_add_u64 v[218:219], v[226:227], 0, s[20:21]
	s_mov_b32 m0, s64
	s_nop 0
	global_load_lds_dwordx4 v[218:219], off
	s_waitcnt vmcnt(8)
	s_waitcnt lgkmcnt(0)
	s_barrier
	s_setprio 1
	v_mfma_f32_16x16x32_bf16 v[78:81], v[58:61], v[180:183], v[78:81]
	v_mfma_f32_16x16x32_bf16 v[74:77], v[66:69], v[180:183], v[74:77]
	v_mfma_f32_16x16x32_bf16 v[46:49], v[58:61], v[188:191], v[46:49]
	v_mfma_f32_16x16x32_bf16 v[42:45], v[66:69], v[188:191], v[42:45]
	v_mfma_f32_16x16x32_bf16 v[30:33], v[58:61], v[196:199], v[30:33]
	v_mfma_f32_16x16x32_bf16 v[26:29], v[66:69], v[196:199], v[26:29]
	v_mfma_f32_16x16x32_bf16 v[14:17], v[58:61], v[204:207], v[14:17]
	v_mfma_f32_16x16x32_bf16 v[10:13], v[66:69], v[204:207], v[10:13]
	v_mfma_f32_16x16x32_bf16 v[78:81], v[62:65], v[184:187], v[78:81]
	v_mfma_f32_16x16x32_bf16 v[74:77], v[70:73], v[184:187], v[74:77]
	v_mfma_f32_16x16x32_bf16 v[46:49], v[62:65], v[192:195], v[46:49]
	v_mfma_f32_16x16x32_bf16 v[42:45], v[70:73], v[192:195], v[42:45]
	v_mfma_f32_16x16x32_bf16 v[30:33], v[62:65], v[200:203], v[30:33]
	v_mfma_f32_16x16x32_bf16 v[26:29], v[70:73], v[200:203], v[26:29]
	v_mfma_f32_16x16x32_bf16 v[14:17], v[62:65], v[208:211], v[14:17]
	v_mfma_f32_16x16x32_bf16 v[10:13], v[70:73], v[208:211], v[10:13]
	v_mfma_f32_16x16x32_bf16 v[50:53], v[146:149], v[180:183], v[50:53]
	v_mfma_f32_16x16x32_bf16 v[62:65], v[150:153], v[184:187], v[50:53]
	v_mfma_f32_16x16x32_bf16 v[50:53], v[172:175], v[180:183], v[54:57]
	v_mfma_f32_16x16x32_bf16 v[38:41], v[146:149], v[188:191], v[38:41]
	v_mfma_f32_16x16x32_bf16 v[34:37], v[172:175], v[188:191], v[34:37]
	v_mfma_f32_16x16x32_bf16 v[22:25], v[146:149], v[196:199], v[22:25]
	v_mfma_f32_16x16x32_bf16 v[18:21], v[172:175], v[196:199], v[18:21]
	v_mfma_f32_16x16x32_bf16 v[6:9], v[146:149], v[204:207], v[6:9]
	v_mfma_f32_16x16x32_bf16 v[2:5], v[172:175], v[204:207], v[2:5]
	v_mfma_f32_16x16x32_bf16 v[58:61], v[176:179], v[184:187], v[50:53]
	v_mfma_f32_16x16x32_bf16 v[38:41], v[150:153], v[192:195], v[38:41]
	v_mfma_f32_16x16x32_bf16 v[34:37], v[176:179], v[192:195], v[34:37]
	v_mfma_f32_16x16x32_bf16 v[22:25], v[150:153], v[200:203], v[22:25]
	v_mfma_f32_16x16x32_bf16 v[18:21], v[176:179], v[200:203], v[18:21]
	v_mfma_f32_16x16x32_bf16 v[6:9], v[150:153], v[208:211], v[6:9]
	v_mfma_f32_16x16x32_bf16 v[2:5], v[176:179], v[208:211], v[2:5]
	s_setprio 0
	s_barrier
	s_add_i32 s41, s41, 2
	s_add_u32 s4, s4, 0x100
	s_addc_u32 s5, s5, 0
	s_add_u32 s39, s39, 0x100
	s_addc_u32 s40, s40, 0
	s_cmp_gt_u32 s41, 13
	s_cbranch_scc0 .LBB0_838
	s_and_b64 vcc, exec, s[22:23]
	s_cbranch_vccz .LBB0_841
	s_barrier

; #define PG8_STAGE(bufoff, gbase, voff) do { _Pragma("unroll") for (int _i = 0; _i < 2; ++_i) \
;         __builtin_amdgcn_global_load_lds((const unsigned*)((const char*)(gbase) + (voff)[_i]), (PG8_LAS unsigned*)(lds + (bufoff) + ldsw + _i * 8192), 16, 0, 0); } while (0)
; #define PG8_LDA(dst, b, h) do { _Pragma("unroll") for (int m = 0; m < 4; ++m) _Pragma("unroll") for (int k = 0; k < 2; ++k) dst[m][k] = *(const PG8_LAS bf16x8*)(lds + PG8_SA(b, h) + aoff + m * 2048 + k * 1024); } while (0)
; #define PG8_LDB(dst, b, h) do { _Pragma("unroll") for (int n = 0; n < 2; ++n) _Pragma("unroll") for (int k = 0; k < 2; ++k) dst[n][k] = *(const PG8_LAS bf16x8*)(lds + PG8_SB(b, h) + boff + n * 2048 + k * 1024); } while (0)
; #define PG8_MMA(ai, bj, At, Bt) do { __builtin_amdgcn_s_setprio(1); _Pragma("unroll") for (int m = 0; m < 4; ++m) _Pragma("unroll") for (int n = 0; n < 2; ++n) _Pragma("unroll") for (int k = 0; k < 2; ++k) \
;         acc[ai][bj][m][n] = __builtin_amdgcn_mfma_f32_16x16x32_bf16(Bt[n][k], At[m][k], acc[ai][bj][m][n], 0, 0, 0); __builtin_amdgcn_s_setprio(0); } while (0)
; #define PG8_WAIT_V(n) asm volatile("s_waitcnt vmcnt(" #n ")" ::: "memory")
; #define PG8_WAIT_L(n) asm volatile("s_waitcnt lgkmcnt(" #n ")" ::: "memory")
; #define PG8_BAR __builtin_amdgcn_s_barrier()
; #define PG8_SCHED __builtin_amdgcn_sched_barrier(0)
; template <class Epi, class Sched, bool ALIGN_EPI = false, bool SP2 = false>
; __device__ __forceinline__ void gemm_phase(PG8_LAS unsigned char* lds, const Gemm g, const Sched& S, const Epi& E) {
;     ...
;             PG8_LDB(B0, 1, 0); PG8_LDB(B1, 1, 1); PG8_SCHED; PG8_LDA(At, 1, 0); PG8_STAGE(PG8_SA(0, 1), a2 + hstep, voffA);
;             PG8_WAIT_V(8); PG8_WAIT_L(0); PG8_BAR; PG8_MMA(0, 0, At, B0); PG8_MMA(0, 1, At, B1); PG8_BAR; PG8_SCHED;
;             PG8_LDA(At, 1, 1); PG8_STAGE(PG8_SB(1, 0), b3, voffB); PG8_STAGE(PG8_SB(1, 1), b3 + hstep, voffB); PG8_STAGE(PG8_SA(1, 0), a3, voffA);
;             PG8_WAIT_V(8); PG8_WAIT_L(0); PG8_BAR; PG8_MMA(1, 0, At, B0); PG8_MMA(1, 1, At, B1); PG8_BAR; PG8_SCHED;
.Lpz5_mid:
	ds_read_b128 v[200:203], v197 offset:32768
	ds_read_b128 v[204:207], v197 offset:33792
	ds_read_b128 v[208:211], v197 offset:34816
	ds_read_b128 v[212:215], v197 offset:35840
	ds_read_b128 v[216:219], v197 offset:36864
	ds_read_b128 v[220:223], v197 offset:37888
	ds_read_b128 v[224:227], v197 offset:38912
	ds_read_b128 v[228:231], v197 offset:39936
	s_add_i32 s84, 0, 0x18000
	v_add_u32_e32 v130, s84, v193
	s_add_i32 s85, 0, 0x1c000
	ds_read_b128 v[138:141], v130
	ds_read_b128 v[142:145], v130 offset:1024
	ds_read_b128 v[146:149], v130 offset:2048
	ds_read_b128 v[150:153], v130 offset:3072
	v_add_u32_e32 v130, s85, v193
	ds_read_b128 v[154:157], v130
	ds_read_b128 v[158:161], v130 offset:1024
	ds_read_b128 v[162:165], v130 offset:2048
	ds_read_b128 v[166:169], v130 offset:3072
	s_add_u32 s44, s44, 0x40000
	s_addc_u32 s45, s45, 0
	s_mov_b32 m0, s60
	v_lshl_add_u64 v[130:131], s[44:45], 0, v[176:177]
	global_load_lds_dwordx4 v[130:131], off
	v_lshl_add_u64 v[130:131], s[44:45], 0, v[172:173]
	s_mov_b32 m0, s61
	s_nop 0
	global_load_lds_dwordx4 v[130:131], off
	s_waitcnt vmcnt(8)
	s_waitcnt lgkmcnt(0)
	s_barrier
	s_setprio 1
	v_mfma_f32_16x16x32_bf16 v[98:101], v[138:141], v[200:203], v[98:101]
	v_mfma_f32_16x16x32_bf16 v[134:137], v[142:145], v[204:207], v[98:101]
	v_mfma_f32_16x16x32_bf16 v[98:101], v[146:149], v[200:203], v[106:109]
	v_mfma_f32_16x16x32_bf16 v[130:133], v[150:153], v[204:207], v[98:101]
	v_mfma_f32_16x16x32_bf16 v[98:101], v[138:141], v[208:211], v[118:121]
	v_mfma_f32_16x16x32_bf16 v[118:121], v[142:145], v[212:215], v[98:101]
	v_mfma_f32_16x16x32_bf16 v[98:101], v[146:149], v[208:211], v[114:117]
	v_mfma_f32_16x16x32_bf16 v[94:97], v[138:141], v[216:219], v[94:97]
	v_mfma_f32_16x16x32_bf16 v[90:93], v[146:149], v[216:219], v[90:93]
	v_mfma_f32_16x16x32_bf16 v[78:81], v[138:141], v[224:227], v[78:81]
	v_mfma_f32_16x16x32_bf16 v[74:77], v[146:149], v[224:227], v[74:77]
	v_mfma_f32_16x16x32_bf16 v[114:117], v[150:153], v[212:215], v[98:101]
	v_mfma_f32_16x16x32_bf16 v[94:97], v[142:145], v[220:223], v[94:97]
	v_mfma_f32_16x16x32_bf16 v[90:93], v[150:153], v[220:223], v[90:93]
	v_mfma_f32_16x16x32_bf16 v[78:81], v[142:145], v[228:231], v[78:81]
	v_mfma_f32_16x16x32_bf16 v[74:77], v[150:153], v[228:231], v[74:77]
	v_mfma_f32_16x16x32_bf16 v[98:101], v[154:157], v[200:203], v[126:129]
	v_mfma_f32_16x16x32_bf16 v[126:129], v[158:161], v[204:207], v[98:101]
	v_mfma_f32_16x16x32_bf16 v[98:101], v[162:165], v[200:203], v[122:125]
	v_mfma_f32_16x16x32_bf16 v[122:125], v[166:169], v[204:207], v[98:101]
	v_mfma_f32_16x16x32_bf16 v[98:101], v[154:157], v[208:211], v[110:113]
	v_mfma_f32_16x16x32_bf16 v[110:113], v[158:161], v[212:215], v[98:101]
	v_mfma_f32_16x16x32_bf16 v[98:101], v[162:165], v[208:211], v[102:105]
	v_mfma_f32_16x16x32_bf16 v[86:89], v[154:157], v[216:219], v[86:89]
	v_mfma_f32_16x16x32_bf16 v[82:85], v[162:165], v[216:219], v[82:85]
	v_mfma_f32_16x16x32_bf16 v[70:73], v[154:157], v[224:227], v[70:73]
	v_mfma_f32_16x16x32_bf16 v[66:69], v[162:165], v[224:227], v[66:69]
	v_mfma_f32_16x16x32_bf16 v[102:105], v[166:169], v[212:215], v[98:101]
	v_mfma_f32_16x16x32_bf16 v[86:89], v[158:161], v[220:223], v[86:89]
	v_mfma_f32_16x16x32_bf16 v[82:85], v[166:169], v[220:223], v[82:85]
	v_mfma_f32_16x16x32_bf16 v[70:73], v[158:161], v[228:231], v[70:73]
	v_mfma_f32_16x16x32_bf16 v[66:69], v[166:169], v[228:231], v[66:69]
	s_setprio 0
	s_barrier
	s_add_i32 s44, s84, s51
	v_lshl_add_u64 v[224:225], v[232:233], 0, s[8:9]
	s_mov_b32 m0, s44
	ds_read_b128 v[98:101], v197 offset:49152
	ds_read_b128 v[106:109], v197 offset:50176
	ds_read_b128 v[200:203], v197 offset:51200
	ds_read_b128 v[204:207], v197 offset:52224
	ds_read_b128 v[208:211], v197 offset:53248
	ds_read_b128 v[212:215], v197 offset:54272
	ds_read_b128 v[216:219], v197 offset:55296
	ds_read_b128 v[220:223], v197 offset:56320
	global_load_lds_dwordx4 v[224:225], off
	s_add_i32 m0, s44, 0x2000
	s_add_u32 s42, s42, 0x40080
	v_lshl_add_u64 v[224:225], v[234:235], 0, s[8:9]
	s_addc_u32 s43, s43, 0
	s_add_i32 s44, s85, s51
	global_load_lds_dwordx4 v[224:225], off
	v_lshl_add_u64 v[224:225], s[42:43], 0, v[174:175]
	s_mov_b32 m0, s44
	s_nop 0
	global_load_lds_dwordx4 v[224:225], off
	v_lshl_add_u64 v[224:225], s[42:43], 0, v[170:171]
	s_add_i32 m0, s44, 0x2000
	s_nop 0
	global_load_lds_dwordx4 v[224:225], off
	v_lshl_add_u64 v[224:225], v[236:237], 0, s[8:9]
	s_mov_b32 m0, s65
	s_nop 0
	global_load_lds_dwordx4 v[224:225], off
	v_lshl_add_u64 v[224:225], v[238:239], 0, s[8:9]
	s_mov_b32 m0, s66
	s_nop 0
	global_load_lds_dwordx4 v[224:225], off
	s_waitcnt vmcnt(8)
	s_waitcnt lgkmcnt(0)
	s_barrier
	s_setprio 1
	v_mfma_f32_16x16x32_bf16 v[62:65], v[138:141], v[98:101], v[62:65]
	v_mfma_f32_16x16x32_bf16 v[58:61], v[146:149], v[98:101], v[58:61]
	v_mfma_f32_16x16x32_bf16 v[46:49], v[138:141], v[200:203], v[46:49]
	v_mfma_f32_16x16x32_bf16 v[42:45], v[146:149], v[200:203], v[42:45]
	v_mfma_f32_16x16x32_bf16 v[30:33], v[138:141], v[208:211], v[30:33]
	v_mfma_f32_16x16x32_bf16 v[26:29], v[146:149], v[208:211], v[26:29]
	v_mfma_f32_16x16x32_bf16 v[14:17], v[138:141], v[216:219], v[14:17]
	v_mfma_f32_16x16x32_bf16 v[10:13], v[146:149], v[216:219], v[10:13]
	v_mfma_f32_16x16x32_bf16 v[62:65], v[142:145], v[106:109], v[62:65]
	v_mfma_f32_16x16x32_bf16 v[58:61], v[150:153], v[106:109], v[58:61]
	v_mfma_f32_16x16x32_bf16 v[46:49], v[142:145], v[204:207], v[46:49]
	v_mfma_f32_16x16x32_bf16 v[42:45], v[150:153], v[204:207], v[42:45]
	v_mfma_f32_16x16x32_bf16 v[30:33], v[142:145], v[212:215], v[30:33]
	v_mfma_f32_16x16x32_bf16 v[26:29], v[150:153], v[212:215], v[26:29]
	v_mfma_f32_16x16x32_bf16 v[14:17], v[142:145], v[220:223], v[14:17]
	v_mfma_f32_16x16x32_bf16 v[10:13], v[150:153], v[220:223], v[10:13]
	v_mfma_f32_16x16x32_bf16 v[54:57], v[154:157], v[98:101], v[54:57]
	v_mfma_f32_16x16x32_bf16 v[50:53], v[162:165], v[98:101], v[50:53]
	v_mfma_f32_16x16x32_bf16 v[38:41], v[154:157], v[200:203], v[38:41]
	v_mfma_f32_16x16x32_bf16 v[34:37], v[162:165], v[200:203], v[34:37]
	v_mfma_f32_16x16x32_bf16 v[22:25], v[154:157], v[208:211], v[22:25]
	v_mfma_f32_16x16x32_bf16 v[18:21], v[162:165], v[208:211], v[18:21]
	v_mfma_f32_16x16x32_bf16 v[6:9], v[154:157], v[216:219], v[6:9]
	v_mfma_f32_16x16x32_bf16 v[2:5], v[162:165], v[216:219], v[2:5]
	v_mfma_f32_16x16x32_bf16 v[54:57], v[158:161], v[106:109], v[54:57]
	v_mfma_f32_16x16x32_bf16 v[50:53], v[166:169], v[106:109], v[50:53]
	v_mfma_f32_16x16x32_bf16 v[38:41], v[158:161], v[204:207], v[38:41]
	v_mfma_f32_16x16x32_bf16 v[34:37], v[166:169], v[204:207], v[34:37]
	v_mfma_f32_16x16x32_bf16 v[22:25], v[158:161], v[212:215], v[22:25]
	v_mfma_f32_16x16x32_bf16 v[18:21], v[166:169], v[212:215], v[18:21]
	v_mfma_f32_16x16x32_bf16 v[6:9], v[158:161], v[220:223], v[6:9]
	v_mfma_f32_16x16x32_bf16 v[2:5], v[166:169], v[220:223], v[2:5]
	s_setprio 0
	s_barrier
	s_add_i32 s42, s83, 2
	s_add_u32 s40, s40, 0x100
	s_addc_u32 s41, s41, 0
	s_cmp_gt_u32 s83, 13
	s_mov_b32 s83, s42
	s_cbranch_scc1 .LBB0_989

; #define PG8_STAGE(bufoff, gbase, voff) do { _Pragma("unroll") for (int _i = 0; _i < 2; ++_i) \
;         __builtin_amdgcn_global_load_lds((const unsigned*)((const char*)(gbase) + (voff)[_i]), (PG8_LAS unsigned*)(lds + (bufoff) + ldsw + _i * 8192), 16, 0, 0); } while (0)
; #define PG8_LDA(dst, b, h) do { _Pragma("unroll") for (int m = 0; m < 4; ++m) _Pragma("unroll") for (int k = 0; k < 2; ++k) dst[m][k] = *(const PG8_LAS bf16x8*)(lds + PG8_SA(b, h) + aoff + m * 2048 + k * 1024); } while (0)
; #define PG8_LDB(dst, b, h) do { _Pragma("unroll") for (int n = 0; n < 2; ++n) _Pragma("unroll") for (int k = 0; k < 2; ++k) dst[n][k] = *(const PG8_LAS bf16x8*)(lds + PG8_SB(b, h) + boff + n * 2048 + k * 1024); } while (0)
; #define PG8_MMA(ai, bj, At, Bt) do { __builtin_amdgcn_s_setprio(1); _Pragma("unroll") for (int m = 0; m < 4; ++m) _Pragma("unroll") for (int n = 0; n < 2; ++n) _Pragma("unroll") for (int k = 0; k < 2; ++k) \
;         acc[ai][bj][m][n] = __builtin_amdgcn_mfma_f32_16x16x32_bf16(Bt[n][k], At[m][k], acc[ai][bj][m][n], 0, 0, 0); __builtin_amdgcn_s_setprio(0); } while (0)
; #define PG8_WAIT_V(n) asm volatile("s_waitcnt vmcnt(" #n ")" ::: "memory")
; #define PG8_WAIT_L(n) asm volatile("s_waitcnt lgkmcnt(" #n ")" ::: "memory")
; #define PG8_BAR __builtin_amdgcn_s_barrier()
; #define PG8_SCHED __builtin_amdgcn_sched_barrier(0)
; template <class Epi, class Sched, bool ALIGN_EPI = false, bool SP2 = false>
; __device__ __forceinline__ void gemm_phase(PG8_LAS unsigned char* lds, const Gemm g, const Sched& S, const Epi& E) {
;     ...
;             PG8_LDB(B0, 1, 0); PG8_LDB(B1, 1, 1); PG8_SCHED; PG8_LDA(At, 1, 0); PG8_STAGE(PG8_SA(0, 1), a2 + hstep, voffA);
;             PG8_WAIT_V(8); PG8_WAIT_L(0); PG8_BAR; PG8_MMA(0, 0, At, B0); PG8_MMA(0, 1, At, B1); PG8_BAR; PG8_SCHED;
.Lpz6_mid:
	ds_read_b128 v[180:183], v194 offset:32768
	ds_read_b128 v[184:187], v194 offset:33792
	ds_read_b128 v[196:199], v194 offset:34816
	ds_read_b128 v[200:203], v194 offset:35840
	ds_read_b128 v[204:207], v194 offset:36864
	ds_read_b128 v[208:211], v194 offset:37888
	ds_read_b128 v[212:215], v194 offset:38912
	ds_read_b128 v[216:219], v194 offset:39936
	s_add_i32 s38, 0, 0x18000
	v_add_u32_e32 v146, s38, v191
	s_add_i32 s39, 0, 0x1c000
	ds_read_b128 v[130:133], v146
	ds_read_b128 v[134:137], v146 offset:1024
	ds_read_b128 v[156:159], v146 offset:2048
	ds_read_b128 v[160:163], v146 offset:3072
	v_add_u32_e32 v146, s39, v191
	ds_read_b128 v[164:167], v146
	ds_read_b128 v[168:171], v146 offset:1024
	ds_read_b128 v[172:175], v146 offset:2048
	ds_read_b128 v[176:179], v146 offset:3072
	s_add_u32 s4, s30, 0xb0000
	s_addc_u32 s5, s31, 0
	s_mov_b32 m0, s47
	v_lshl_add_u64 v[226:227], s[4:5], 0, v[138:139]
	global_load_lds_dwordx4 v[226:227], off
	v_lshl_add_u64 v[226:227], s[4:5], 0, v[142:143]
	s_mov_b32 m0, s48
	s_nop 0
	global_load_lds_dwordx4 v[226:227], off
	s_waitcnt vmcnt(8)
	s_waitcnt lgkmcnt(0)
	s_barrier
	s_setprio 1
	v_mfma_f32_16x16x32_bf16 v[126:129], v[130:133], v[180:183], v[126:129]
	v_mfma_f32_16x16x32_bf16 v[122:125], v[156:159], v[180:183], v[122:125]
	v_mfma_f32_16x16x32_bf16 v[110:113], v[130:133], v[196:199], v[110:113]
	v_mfma_f32_16x16x32_bf16 v[106:109], v[156:159], v[196:199], v[106:109]
	v_mfma_f32_16x16x32_bf16 v[94:97], v[130:133], v[204:207], v[94:97]
	v_mfma_f32_16x16x32_bf16 v[90:93], v[156:159], v[204:207], v[90:93]
	v_mfma_f32_16x16x32_bf16 v[78:81], v[130:133], v[212:215], v[78:81]
	v_mfma_f32_16x16x32_bf16 v[74:77], v[156:159], v[212:215], v[74:77]
	v_mfma_f32_16x16x32_bf16 v[126:129], v[134:137], v[184:187], v[126:129]
	v_mfma_f32_16x16x32_bf16 v[122:125], v[160:163], v[184:187], v[122:125]
	v_mfma_f32_16x16x32_bf16 v[110:113], v[134:137], v[200:203], v[110:113]
	v_mfma_f32_16x16x32_bf16 v[106:109], v[160:163], v[200:203], v[106:109]
	v_mfma_f32_16x16x32_bf16 v[94:97], v[134:137], v[208:211], v[94:97]
	v_mfma_f32_16x16x32_bf16 v[90:93], v[160:163], v[208:211], v[90:93]
	v_mfma_f32_16x16x32_bf16 v[78:81], v[134:137], v[216:219], v[78:81]
	v_mfma_f32_16x16x32_bf16 v[74:77], v[160:163], v[216:219], v[74:77]
	v_mfma_f32_16x16x32_bf16 v[118:121], v[164:167], v[180:183], v[118:121]
	v_mfma_f32_16x16x32_bf16 v[114:117], v[172:175], v[180:183], v[114:117]
	v_mfma_f32_16x16x32_bf16 v[102:105], v[164:167], v[196:199], v[102:105]
	v_mfma_f32_16x16x32_bf16 v[98:101], v[172:175], v[196:199], v[98:101]
	v_mfma_f32_16x16x32_bf16 v[86:89], v[164:167], v[204:207], v[86:89]
	v_mfma_f32_16x16x32_bf16 v[82:85], v[172:175], v[204:207], v[82:85]
	v_mfma_f32_16x16x32_bf16 v[70:73], v[164:167], v[212:215], v[70:73]
	v_mfma_f32_16x16x32_bf16 v[66:69], v[172:175], v[212:215], v[66:69]
	v_mfma_f32_16x16x32_bf16 v[118:121], v[168:171], v[184:187], v[118:121]
	v_mfma_f32_16x16x32_bf16 v[114:117], v[176:179], v[184:187], v[114:117]
	v_mfma_f32_16x16x32_bf16 v[102:105], v[168:171], v[200:203], v[102:105]
	v_mfma_f32_16x16x32_bf16 v[98:101], v[176:179], v[200:203], v[98:101]
	v_mfma_f32_16x16x32_bf16 v[86:89], v[168:171], v[208:211], v[86:89]
	v_mfma_f32_16x16x32_bf16 v[82:85], v[176:179], v[208:211], v[82:85]
	v_mfma_f32_16x16x32_bf16 v[70:73], v[168:171], v[216:219], v[70:73]
	v_mfma_f32_16x16x32_bf16 v[66:69], v[176:179], v[216:219], v[66:69]
	s_setprio 0
	s_barrier
; #define PG8_STAGE(bufoff, gbase, voff) do { _Pragma("unroll") for (int _i = 0; _i < 2; ++_i) \
;         __builtin_amdgcn_global_load_lds((const unsigned*)((const char*)(gbase) + (voff)[_i]), (PG8_LAS unsigned*)(lds + (bufoff) + ldsw + _i * 8192), 16, 0, 0); } while (0)
; #define PG8_LDA(dst, b, h) do { _Pragma("unroll") for (int m = 0; m < 4; ++m) _Pragma("unroll") for (int k = 0; k < 2; ++k) dst[m][k] = *(const PG8_LAS bf16x8*)(lds + PG8_SA(b, h) + aoff + m * 2048 + k * 1024); } while (0)
; #define PG8_MMA(ai, bj, At, Bt) do { __builtin_amdgcn_s_setprio(1); _Pragma("unroll") for (int m = 0; m < 4; ++m) _Pragma("unroll") for (int n = 0; n < 2; ++n) _Pragma("unroll") for (int k = 0; k < 2; ++k) \
;         acc[ai][bj][m][n] = __builtin_amdgcn_mfma_f32_16x16x32_bf16(Bt[n][k], At[m][k], acc[ai][bj][m][n], 0, 0, 0); __builtin_amdgcn_s_setprio(0); } while (0)
; #define PG8_WAIT_V(n) asm volatile("s_waitcnt vmcnt(" #n ")" ::: "memory")
; #define PG8_WAIT_L(n) asm volatile("s_waitcnt lgkmcnt(" #n ")" ::: "memory")
; #define PG8_BAR __builtin_amdgcn_s_barrier()
; #define PG8_SCHED __builtin_amdgcn_sched_barrier(0)
; template <class Epi, class Sched, bool ALIGN_EPI = false, bool SP2 = false>
; __device__ __forceinline__ void gemm_phase(PG8_LAS unsigned char* lds, const Gemm g, const Sched& S, const Epi& E) {
;     ...
;             PG8_LDA(At, 1, 1); PG8_STAGE(PG8_SB(1, 0), b3, voffB); PG8_STAGE(PG8_SB(1, 1), b3 + hstep, voffB); PG8_STAGE(PG8_SA(1, 0), a3, voffA);
;             PG8_WAIT_V(8); PG8_WAIT_L(0); PG8_BAR; PG8_MMA(1, 0, At, B0); PG8_MMA(1, 1, At, B1); PG8_BAR; PG8_SCHED;
;     ...
;         if constexpr (ALIGN_EPI) { if (wr == 0) PG8_BAR; }
	s_add_i32 s4, s38, s44
	v_lshl_add_u64 v[188:189], v[188:189], 0, s[18:19]
	s_mov_b32 m0, s4
	ds_read_b128 v[180:183], v194 offset:49152
	ds_read_b128 v[184:187], v194 offset:50176
	ds_read_b128 v[196:199], v194 offset:51200
	ds_read_b128 v[200:203], v194 offset:52224
	ds_read_b128 v[204:207], v194 offset:53248
	ds_read_b128 v[208:211], v194 offset:54272
	ds_read_b128 v[212:215], v194 offset:55296
	ds_read_b128 v[216:219], v194 offset:56320
	global_load_lds_dwordx4 v[188:189], off
	s_add_i32 m0, s4, 0x2000
	s_add_u32 s4, s6, 0xb0080
	v_lshl_add_u64 v[188:189], v[220:221], 0, s[18:19]
	s_addc_u32 s5, s7, 0
	s_add_i32 s6, s39, s44
	global_load_lds_dwordx4 v[188:189], off
	v_lshl_add_u64 v[188:189], s[4:5], 0, v[140:141]
	s_mov_b32 m0, s6
	s_nop 0
	global_load_lds_dwordx4 v[188:189], off
	v_lshl_add_u64 v[188:189], s[4:5], 0, v[144:145]
	s_add_i32 m0, s6, 0x2000
	s_nop 0
	global_load_lds_dwordx4 v[188:189], off
	v_lshl_add_u64 v[188:189], v[222:223], 0, s[20:21]
	s_mov_b32 m0, s55
	s_nop 0
	global_load_lds_dwordx4 v[188:189], off
	v_lshl_add_u64 v[188:189], v[224:225], 0, s[20:21]
	s_mov_b32 m0, s56
	s_nop 0
	global_load_lds_dwordx4 v[188:189], off
	s_waitcnt vmcnt(8)
	s_waitcnt lgkmcnt(0)
	s_barrier
	s_setprio 1
	v_mfma_f32_16x16x32_bf16 v[62:65], v[130:133], v[180:183], v[62:65]
	v_mfma_f32_16x16x32_bf16 v[58:61], v[156:159], v[180:183], v[58:61]
	v_mfma_f32_16x16x32_bf16 v[46:49], v[130:133], v[196:199], v[46:49]
	v_mfma_f32_16x16x32_bf16 v[42:45], v[156:159], v[196:199], v[42:45]
	v_mfma_f32_16x16x32_bf16 v[30:33], v[130:133], v[204:207], v[30:33]
	v_mfma_f32_16x16x32_bf16 v[26:29], v[156:159], v[204:207], v[26:29]
	v_mfma_f32_16x16x32_bf16 v[14:17], v[130:133], v[212:215], v[14:17]
	v_mfma_f32_16x16x32_bf16 v[10:13], v[156:159], v[212:215], v[10:13]
	v_mfma_f32_16x16x32_bf16 v[62:65], v[134:137], v[184:187], v[62:65]
	v_mfma_f32_16x16x32_bf16 v[58:61], v[160:163], v[184:187], v[58:61]
	v_mfma_f32_16x16x32_bf16 v[46:49], v[134:137], v[200:203], v[46:49]
	v_mfma_f32_16x16x32_bf16 v[42:45], v[160:163], v[200:203], v[42:45]
	v_mfma_f32_16x16x32_bf16 v[30:33], v[134:137], v[208:211], v[30:33]
	v_mfma_f32_16x16x32_bf16 v[26:29], v[160:163], v[208:211], v[26:29]
	v_mfma_f32_16x16x32_bf16 v[14:17], v[134:137], v[216:219], v[14:17]
	v_mfma_f32_16x16x32_bf16 v[10:13], v[160:163], v[216:219], v[10:13]
	v_mfma_f32_16x16x32_bf16 v[54:57], v[164:167], v[180:183], v[54:57]
	v_mfma_f32_16x16x32_bf16 v[50:53], v[172:175], v[180:183], v[50:53]
	v_mfma_f32_16x16x32_bf16 v[38:41], v[164:167], v[196:199], v[38:41]
	v_mfma_f32_16x16x32_bf16 v[34:37], v[172:175], v[196:199], v[34:37]
	v_mfma_f32_16x16x32_bf16 v[22:25], v[164:167], v[204:207], v[22:25]
	v_mfma_f32_16x16x32_bf16 v[18:21], v[172:175], v[204:207], v[18:21]
	v_mfma_f32_16x16x32_bf16 v[6:9], v[164:167], v[212:215], v[6:9]
	v_mfma_f32_16x16x32_bf16 v[2:5], v[172:175], v[212:215], v[2:5]
	v_mfma_f32_16x16x32_bf16 v[54:57], v[168:171], v[184:187], v[54:57]
	v_mfma_f32_16x16x32_bf16 v[50:53], v[176:179], v[184:187], v[50:53]
	v_mfma_f32_16x16x32_bf16 v[38:41], v[168:171], v[200:203], v[38:41]
	v_mfma_f32_16x16x32_bf16 v[34:37], v[176:179], v[200:203], v[34:37]
	v_mfma_f32_16x16x32_bf16 v[22:25], v[168:171], v[208:211], v[22:25]
	v_mfma_f32_16x16x32_bf16 v[18:21], v[176:179], v[208:211], v[18:21]
	v_mfma_f32_16x16x32_bf16 v[6:9], v[168:171], v[216:219], v[6:9]
	v_mfma_f32_16x16x32_bf16 v[2:5], v[176:179], v[216:219], v[2:5]
	s_setprio 0
	s_barrier
	s_add_i32 s37, s37, 2
	s_add_u32 s35, s35, 0x100
	s_addc_u32 s36, s36, 0
	s_cmp_gt_u32 s37, 41
	s_mov_b64 s[4:5], s[0:1]
	s_cbranch_scc0 .LBB0_1069
	s_and_b64 vcc, exec, s[22:23]
	s_cbranch_vccz .LBB0_1072
	s_barrier
